# P0: b_ada and forget-weight-column loads issued before the GEMV loop (their latency was exposed after the reduction), on p0r
# baseline (speedup 1.0000x reference)
; #define LAS __attribute__((address_space(3)))
; template <int LO, int HI> __global__ void __launch_bounds__(NWAVES * 64, 2) fox_fwd(Args args) {
;     ...
;             const int col = bx * 16 + (lane & 15), kpar = lane >> 4;
;             float acc[8];
; #pragma unroll
;             for (int b = 0; b < 8; ++b) acc[b] = 0.f;
; #pragma unroll 8
;             for (int kk = 0; kk < 32; ++kk) { const int k = wave * 128 + 4 * kk + kpar; const float wv = w_ada[(size_t)k * 3072 + col];
;                 const f32x4 c0 = *(const LAS f32x4*)(ct + k * 8), c1 = *(const LAS f32x4*)(ct + k * 8 + 4);
;                 acc[0] += c0[0] * wv; acc[1] += c0[1] * wv; acc[2] += c0[2] * wv; acc[3] += c0[3] * wv; acc[4] += c1[0] * wv; acc[5] += c1[1] * wv; acc[6] += c1[2] * wv; acc[7] += c1[3] * wv; }
; #pragma unroll
;             for (int b = 0; b < 8; ++b) { acc[b] += __shfl_xor(acc[b], 16); acc[b] += __shfl_xor(acc[b], 32); if (lane < 16) red[(wave * 8 + b) * 16 + lane] = acc[b]; }
;             __syncthreads();
;             if (tid < 128) { const int b = tid >> 4, cl = tid & 15; float s = b_ada[bx * 16 + cl];
; #pragma unroll
;                 for (int w = 0; w < 8; ++w) s += red[(w * 8 + b) * 16 + cl];
;                 ADA[b * 3072 + bx * 16 + cl] = s; }
;             __syncthreads();
;         }
;         {
;             const int i = bx * NWAVES * 64 + tid; if (i < 8192) { const int j = i >> 10, k = i & 1023; WF[i] = w_in[(size_t)k * INW + SRC_F + j]; }
.LBB0_19:
	s_or_b64 exec, exec, s[14:15]
	s_waitcnt lgkmcnt(0)
	v_mov_b32_e32 v6, s6
	s_lshl_b32 s6, s27, 4
	v_and_b32_e32 v1, 15, v2
	v_or_b32_e32 v4, s6, v1
	s_lshl_b32 s5, s26, 12
	v_mov_b32_e32 v7, s7
	v_lshrrev_b32_e32 v8, 4, v16
	v_ashrrev_i32_e32 v5, 31, v4
	s_add_i32 s5, s5, 0
	v_mov_b32_e32 v12, 0
	v_lshl_or_b32 v3, s26, 7, v8
	v_lshl_add_u64 v[14:15], v[4:5], 2, v[6:7]
	v_mov_b32_e32 v100, s12
	v_mov_b32_e32 v101, s13
	v_lshl_add_u64 v[100:101], v[4:5], 2, v[100:101]
	global_load_dword v102, v[100:101], off
	v_lshl_add_u32 v104, s27, 9, v2
	s_movk_i32 s20, 0x2000
	v_cmp_gt_i32_e32 vcc, s20, v104
	s_and_saveexec_b64 s[16:17], vcc
	v_and_b32_e32 v105, 0x3ff, v104
	v_mul_u32_u24_e32 v105, 0x1808, v105
	v_ashrrev_i32_e32 v106, 10, v104
	v_lshlrev_b32_e32 v108, 2, v105
	v_mov_b32_e32 v109, 0
	v_ashrrev_i32_e32 v107, 31, v106
	v_lshl_add_u64 v[108:109], s[8:9], 0, v[108:109]
	v_lshl_add_u64 v[106:107], v[106:107], 2, v[108:109]
	v_add_co_u32_e32 v106, vcc, 0x1000, v106
	s_nop 1
	v_addc_co_u32_e32 v107, vcc, 0, v107, vcc
	global_load_dword v103, v[106:107], off offset:2048
	s_or_b64 exec, exec, s[16:17]
	s_mov_b32 s4, 0
	v_lshl_add_u32 v17, v8, 5, s5
	s_movk_i32 s5, 0x3000
	v_mov_b32_e32 v13, v12
	v_mov_b32_e32 v10, v12
	v_mov_b32_e32 v11, v12
	v_mov_b32_e32 v8, v12
	v_mov_b32_e32 v9, v12
	v_mov_b32_e32 v6, v12
	v_mov_b32_e32 v7, v12
	s_barrier

; template <int LO, int HI> __global__ void __launch_bounds__(NWAVES * 64, 2) fox_fwd(Args args) {
;     ...
;             if (tid < 128) { const int b = tid >> 4, cl = tid & 15; float s = b_ada[bx * 16 + cl];
; #pragma unroll
;                 for (int w = 0; w < 8; ++w) s += red[(w * 8 + b) * 16 + cl];
;                 ADA[b * 3072 + bx * 16 + cl] = s; }
.LBB0_37:
	s_or_b64 exec, exec, s[4:5]
	s_movk_i32 s4, 0x80
	v_cmp_gt_i32_e32 vcc, s4, v2
	s_waitcnt lgkmcnt(0)
	s_barrier
	s_and_saveexec_b64 s[4:5], vcc
	s_cbranch_execz .LBB0_39
	v_and_b32_e32 v4, 0x3ffffff0, v2
	v_lshlrev_b32_e32 v5, 2, v1
	v_lshrrev_b32_e32 v6, 4, v2
	s_movk_i32 s7, 0xc00
	v_lshlrev_b32_e32 v4, 2, v4
	v_mul_lo_u32 v6, v6, s7
	v_add3_u32 v10, 0, v4, v5
	v_add_u32_e32 v12, s6, v6
	ds_read2st64_b32 v[4:5], v10 offset0:128 offset1:130
	ds_read2st64_b32 v[6:7], v10 offset0:132 offset1:134
	ds_read2st64_b32 v[8:9], v10 offset0:136 offset1:138
	ds_read2st64_b32 v[10:11], v10 offset0:140 offset1:142
	v_or_b32_e32 v12, v12, v1
	v_ashrrev_i32_e32 v13, 31, v12
	s_waitcnt vmcnt(0) lgkmcnt(3)
	v_add_f32_e32 v1, v102, v4
	v_add_f32_e32 v1, v1, v5
	s_waitcnt lgkmcnt(2)
	v_add_f32_e32 v1, v1, v6
	v_add_f32_e32 v1, v1, v7
	s_waitcnt lgkmcnt(1)
	v_add_f32_e32 v1, v1, v8
	v_add_f32_e32 v1, v1, v9
	s_waitcnt lgkmcnt(0)
	v_add_f32_e32 v1, v1, v10
	v_add_f32_e32 v1, v1, v11
	v_lshl_add_u64 v[4:5], v[12:13], 2, s[10:11]
	global_store_dword v[4:5], v1, off

; template <int LO, int HI> __global__ void __launch_bounds__(NWAVES * 64, 2) fox_fwd(Args args) {
;     ...
;             const int i = bx * NWAVES * 64 + tid; if (i < 8192) { const int j = i >> 10, k = i & 1023; WF[i] = w_in[(size_t)k * INW + SRC_F + j]; }
.LBB0_40:
	v_lshl_add_u32 v4, s27, 9, v2
	s_movk_i32 s4, 0x2000
	v_cmp_gt_i32_e32 vcc, s4, v4
	s_and_saveexec_b64 s[4:5], vcc
	s_cbranch_execz .LBB0_42
	v_ashrrev_i32_e32 v5, 31, v4
	v_lshl_add_u64 v[4:5], v[4:5], 2, s[10:11]
	v_add_co_u32_e32 v4, vcc, 0x20000, v4
	s_nop 1
	v_addc_co_u32_e32 v5, vcc, 0, v5, vcc
	s_waitcnt vmcnt(0)
	global_store_dword v[4:5], v103, off
